# gated-branch GEMM epilogue: the 16 serialized g0 gate loads per z=0 unit issued four at a time beside the g1 loads (into dead fragment registers)
# speedup vs baseline: 1.0022x; 1.0022x over previous
; __device__ __forceinline__ u32x4 pack8(const f32x4 a, const f32x4 b) { u32x4 w; w.x = cvt_pk_bf16(a[0], a[1]); w.y = cvt_pk_bf16(a[2], a[3]); w.z = cvt_pk_bf16(b[0], b[1]); w.w = cvt_pk_bf16(b[2], b[3]); return w; }
; __device__ __forceinline__ float bflo(unsigned w) { return __uint_as_float(w << 16); }
; __device__ __forceinline__ float bfhi(unsigned w) { return __uint_as_float(w & 0xffff0000u); }
;     __device__ __forceinline__ void operator()(f32x4 (&acc)[2][2][4][2], const Unit& u, int wr, int wc, int fr, int fq) const {
;     ...
;             u32x4 g1v[2][2];
; #pragma unroll
;             for (int mm = 0; mm < 2; ++mm)
; #pragma unroll
;                 for (int bj = 0; bj < 2; ++bj) g1v[mm][bj] = *(const u32x4*)(gate + (size_t)(row0 + ai * HALF + (2 * mh + mm) * 16) * 2048 + 1024 + col0 + bj * HALF);
; #pragma unroll
;             for (int mm = 0; mm < 2; ++mm)
; #pragma unroll
;                 for (int bj = 0; bj < 2; ++bj) { const int m = 2 * mh + mm; const int r = row0 + ai * HALF + m * 16; const u32x4 g1 = g1v[mm][bj];
;                     const f32x4 g1a = {bflo(g1.x), bfhi(g1.x), bflo(g1.y), bfhi(g1.y)}, g1b = {bflo(g1.z), bfhi(g1.z), bflo(g1.w), bfhi(g1.w)};
;                     if (u.z == 0) {
;                         const u32x4 g0 = *(const u32x4*)(gate + (size_t)r * 2048 + col0 + bj * HALF);
;                         const f32x4 g0a = {bflo(g0.x), bfhi(g0.x), bflo(g0.y), bfhi(g0.y)}, g0b = {bflo(g0.z), bfhi(g0.z), bflo(g0.w), bfhi(g0.w)};
; #pragma unroll
;                         for (int i = 0; i < 4; ++i) { acc[ai][bj][m][0][i] *= g0a[i] * __builtin_amdgcn_rcpf(__builtin_fmaxf(g1a[i], 1e-30f)); acc[ai][bj][m][1][i] *= g0b[i] * __builtin_amdgcn_rcpf(__builtin_fmaxf(g1b[i], 1e-30f)); }
;                     } else {
;                         *(u32x4*)(merged + (size_t)r * 1024 + col0 + bj * HALF) = pack8(acc[ai][bj][m][0] * g1a, acc[ai][bj][m][1] * g1b); }
.LBB0_770:
	v_lshl_add_u32 v170, s74, 8, v196
	v_lshl_or_b32 v168, s49, 8, v198
	v_ashrrev_i32_e32 v171, 31, v170
	v_ashrrev_i32_e32 v169, 31, v168
	v_lshlrev_b64 v[146:147], 12, v[170:171]
	v_or_b32_e32 v176, 16, v170
	v_lshl_add_u64 v[146:147], s[46:47], 0, v[146:147]
	v_lshlrev_b64 v[172:173], 1, v[168:169]
	v_ashrrev_i32_e32 v177, 31, v176
	v_lshl_add_u64 v[184:185], v[146:147], 0, v[172:173]
	v_lshlrev_b64 v[146:147], 12, v[176:177]
	v_lshl_add_u64 v[146:147], s[46:47], 0, v[146:147]
	v_lshl_add_u64 v[174:175], v[146:147], 0, v[172:173]
	global_load_dwordx4 v[200:203], v[184:185], off offset:2048
	global_load_dwordx4 v[154:157], v[184:185], off offset:2304
	global_load_dwordx4 v[150:153], v[174:175], off offset:2048
	global_load_dwordx4 v[146:149], v[174:175], off offset:2304
	global_load_dwordx4 v[222:225], v[184:185], off
	global_load_dwordx4 v[226:229], v[184:185], off offset:256
	global_load_dwordx4 v[230:233], v[174:175], off
	global_load_dwordx4 v[234:237], v[174:175], off offset:256
	s_cmp_lg_u32 s48, 0
	v_lshlrev_b64 v[182:183], 11, v[170:171]
	s_cselect_b64 s[64:65], -1, 0
	v_lshl_add_u64 v[182:183], s[52:53], 0, v[182:183]
	s_and_b64 vcc, exec, s[64:65]
	v_lshl_add_u64 v[186:187], v[168:169], 1, v[182:183]
	s_waitcnt vmcnt(0)
	v_lshlrev_b32_e32 v194, 16, v200
	v_and_b32_e32 v195, 0xffff0000, v200
	v_lshlrev_b32_e32 v190, 16, v201
	v_and_b32_e32 v191, 0xffff0000, v201
	v_lshlrev_b32_e32 v192, 16, v202
	v_and_b32_e32 v193, 0xffff0000, v202
	v_lshlrev_b32_e32 v188, 16, v203
	v_and_b32_e32 v189, 0xffff0000, v203
	s_cbranch_vccz .LBB0_823
	v_pk_mul_f32 v[182:183], v[144:145], v[190:191]
	v_pk_mul_f32 v[200:201], v[142:143], v[194:195]
	v_pk_mul_f32 v[204:205], v[140:141], v[188:189]
	v_pk_mul_f32 v[202:203], v[138:139], v[192:193]
	v_cvt_pk_bf16_f32 v200, v200, v201
	v_cvt_pk_bf16_f32 v201, v182, v183
	v_cvt_pk_bf16_f32 v202, v202, v203
	v_cvt_pk_bf16_f32 v203, v204, v205
	global_store_dwordx4 v[186:187], v[200:203], off
	s_cbranch_execnz .LBB0_773
.LBB0_772:
	v_max_f32_e32 v171, v194, v194
	v_max_f32_e32 v171, 0xda24260, v171
	v_rcp_f32_e32 v182, v171
	v_max_f32_e32 v171, v192, v192
	v_max_f32_e32 v171, 0xda24260, v171
	v_rcp_f32_e32 v192, v171
	v_max_f32_e32 v171, v195, v195
	v_max_f32_e32 v171, 0xda24260, v171
	v_rcp_f32_e32 v183, v171
	v_max_f32_e32 v171, v193, v193
	v_max_f32_e32 v171, 0xda24260, v171
	v_rcp_f32_e32 v193, v171
	v_max_f32_e32 v171, v190, v190
	v_max_f32_e32 v171, 0xda24260, v171
	s_waitcnt vmcnt(0)
	v_lshlrev_b32_e32 v194, 16, v222
	v_and_b32_e32 v195, 0xffff0000, v222
	v_pk_mul_f32 v[182:183], v[182:183], v[194:195]
	v_lshlrev_b32_e32 v190, 16, v223
	v_pk_mul_f32 v[142:143], v[142:143], v[182:183]
	v_lshlrev_b32_e32 v182, 16, v224
	v_and_b32_e32 v183, 0xffff0000, v224
	v_pk_mul_f32 v[182:183], v[192:193], v[182:183]
	s_nop 0
	v_pk_mul_f32 v[138:139], v[138:139], v[182:183]
	v_rcp_f32_e32 v182, v171
	v_max_f32_e32 v171, v188, v188
	v_max_f32_e32 v171, 0xda24260, v171
	v_rcp_f32_e32 v188, v171
	v_max_f32_e32 v171, v191, v191
	v_max_f32_e32 v171, 0xda24260, v171
	v_rcp_f32_e32 v183, v171
	v_max_f32_e32 v171, v189, v189
	v_max_f32_e32 v171, 0xda24260, v171
	v_rcp_f32_e32 v189, v171
	v_and_b32_e32 v191, 0xffff0000, v223
	v_pk_mul_f32 v[182:183], v[182:183], v[190:191]
	s_nop 0
	v_pk_mul_f32 v[144:145], v[144:145], v[182:183]
	v_lshlrev_b32_e32 v182, 16, v225
	v_and_b32_e32 v183, 0xffff0000, v225
	v_pk_mul_f32 v[182:183], v[188:189], v[182:183]
	s_nop 0
	v_pk_mul_f32 v[140:141], v[140:141], v[182:183]

; __device__ __forceinline__ float bflo(unsigned w) { return __uint_as_float(w << 16); }
; __device__ __forceinline__ float bfhi(unsigned w) { return __uint_as_float(w & 0xffff0000u); }
;     __device__ __forceinline__ void operator()(f32x4 (&acc)[2][2][4][2], const Unit& u, int wr, int wc, int fr, int fq) const {
;     ...
;                 for (int bj = 0; bj < 2; ++bj) { const int m = 2 * mh + mm; const int r = row0 + ai * HALF + m * 16; const u32x4 g1 = g1v[mm][bj];
;                     const f32x4 g1a = {bflo(g1.x), bfhi(g1.x), bflo(g1.y), bfhi(g1.y)}, g1b = {bflo(g1.z), bfhi(g1.z), bflo(g1.w), bfhi(g1.w)};
;                     if (u.z == 0) {
;                         const u32x4 g0 = *(const u32x4*)(gate + (size_t)r * 2048 + col0 + bj * HALF);
;                         const f32x4 g0a = {bflo(g0.x), bfhi(g0.x), bflo(g0.y), bfhi(g0.y)}, g0b = {bflo(g0.z), bfhi(g0.z), bflo(g0.w), bfhi(g0.w)};
; #pragma unroll
;                         for (int i = 0; i < 4; ++i) { acc[ai][bj][m][0][i] *= g0a[i] * __builtin_amdgcn_rcpf(__builtin_fmaxf(g1a[i], 1e-30f)); acc[ai][bj][m][1][i] *= g0b[i] * __builtin_amdgcn_rcpf(__builtin_fmaxf(g1b[i], 1e-30f)); }
.LBB0_775:
	v_max_f32_e32 v157, v190, v190
	v_max_f32_e32 v157, 0xda24260, v157
	v_max_f32_e32 v156, v192, v192
	v_rcp_f32_e32 v182, v157
	v_max_f32_e32 v157, v193, v193
	v_max_f32_e32 v156, 0xda24260, v156
	v_max_f32_e32 v157, 0xda24260, v157
	v_rcp_f32_e32 v156, v156
	v_rcp_f32_e32 v157, v157
	v_max_f32_e32 v154, v154, v154
	v_max_f32_e32 v155, v155, v155
	v_max_f32_e32 v154, 0xda24260, v154
	v_max_f32_e32 v155, 0xda24260, v155
	v_rcp_f32_e32 v154, v154
	v_rcp_f32_e32 v155, v155
	s_waitcnt vmcnt(0)
	v_lshlrev_b32_e32 v192, 16, v226
	v_and_b32_e32 v193, 0xffff0000, v226
	v_pk_mul_f32 v[156:157], v[156:157], v[192:193]
	s_nop 0
	v_pk_mul_f32 v[110:111], v[110:111], v[156:157]
	v_max_f32_e32 v156, v191, v191
	v_max_f32_e32 v156, 0xda24260, v156
	v_rcp_f32_e32 v183, v156
	v_lshlrev_b32_e32 v156, 16, v228
	v_and_b32_e32 v157, 0xffff0000, v228
	v_pk_mul_f32 v[156:157], v[182:183], v[156:157]
	s_nop 0
	v_pk_mul_f32 v[106:107], v[106:107], v[156:157]
	v_max_f32_e32 v156, v188, v188
	v_max_f32_e32 v157, v189, v189
	v_max_f32_e32 v156, 0xda24260, v156
	v_max_f32_e32 v157, 0xda24260, v157
	v_rcp_f32_e32 v156, v156
	v_rcp_f32_e32 v157, v157
	v_lshlrev_b32_e32 v182, 16, v227
	v_and_b32_e32 v183, 0xffff0000, v227
	v_pk_mul_f32 v[156:157], v[156:157], v[182:183]
	s_nop 0
	v_pk_mul_f32 v[112:113], v[112:113], v[156:157]
	v_lshlrev_b32_e32 v156, 16, v229
	v_and_b32_e32 v157, 0xffff0000, v229
	v_pk_mul_f32 v[154:155], v[154:155], v[156:157]
	s_nop 0
	v_pk_mul_f32 v[108:109], v[108:109], v[154:155]

; __device__ __forceinline__ float bflo(unsigned w) { return __uint_as_float(w << 16); }
; __device__ __forceinline__ float bfhi(unsigned w) { return __uint_as_float(w & 0xffff0000u); }
;     __device__ __forceinline__ void operator()(f32x4 (&acc)[2][2][4][2], const Unit& u, int wr, int wc, int fr, int fq) const {
;     ...
;                 for (int bj = 0; bj < 2; ++bj) { const int m = 2 * mh + mm; const int r = row0 + ai * HALF + m * 16; const u32x4 g1 = g1v[mm][bj];
;                     const f32x4 g1a = {bflo(g1.x), bfhi(g1.x), bflo(g1.y), bfhi(g1.y)}, g1b = {bflo(g1.z), bfhi(g1.z), bflo(g1.w), bfhi(g1.w)};
;                     if (u.z == 0) {
;                         const u32x4 g0 = *(const u32x4*)(gate + (size_t)r * 2048 + col0 + bj * HALF);
;                         const f32x4 g0a = {bflo(g0.x), bfhi(g0.x), bflo(g0.y), bfhi(g0.y)}, g0b = {bflo(g0.z), bfhi(g0.z), bflo(g0.w), bfhi(g0.w)};
; #pragma unroll
;                         for (int i = 0; i < 4; ++i) { acc[ai][bj][m][0][i] *= g0a[i] * __builtin_amdgcn_rcpf(__builtin_fmaxf(g1a[i], 1e-30f)); acc[ai][bj][m][1][i] *= g0b[i] * __builtin_amdgcn_rcpf(__builtin_fmaxf(g1b[i], 1e-30f)); }
.LBB0_778:
	v_max_f32_e32 v171, v176, v176
	v_max_f32_e32 v171, 0xda24260, v171
	v_rcp_f32_e32 v176, v171
	v_max_f32_e32 v171, v177, v177
	v_max_f32_e32 v171, 0xda24260, v171
	v_max_f32_e32 v156, v156, v156
	v_rcp_f32_e32 v177, v171
	v_max_f32_e32 v157, v157, v157
	v_max_f32_e32 v156, 0xda24260, v156
	v_max_f32_e32 v157, 0xda24260, v157
	v_rcp_f32_e32 v156, v156
	v_rcp_f32_e32 v157, v157
	v_max_f32_e32 v154, v154, v154
	v_max_f32_e32 v155, v155, v155
	v_max_f32_e32 v154, 0xda24260, v154
	v_max_f32_e32 v155, 0xda24260, v155
	v_rcp_f32_e32 v154, v154
	v_max_f32_e32 v152, v152, v152
	v_rcp_f32_e32 v155, v155
	v_max_f32_e32 v153, v153, v153
	v_max_f32_e32 v152, 0xda24260, v152
	v_max_f32_e32 v153, 0xda24260, v153
	v_rcp_f32_e32 v152, v152
	v_rcp_f32_e32 v153, v153
	s_waitcnt vmcnt(0)
	v_lshlrev_b32_e32 v182, 16, v230
	v_and_b32_e32 v183, 0xffff0000, v230
	v_pk_mul_f32 v[176:177], v[176:177], v[182:183]
	s_nop 0
	v_pk_mul_f32 v[134:135], v[134:135], v[176:177]
	v_lshlrev_b32_e32 v176, 16, v232
	v_and_b32_e32 v177, 0xffff0000, v232
	v_pk_mul_f32 v[156:157], v[156:157], v[176:177]
	s_nop 0
	v_pk_mul_f32 v[130:131], v[130:131], v[156:157]
	v_lshlrev_b32_e32 v156, 16, v231
	v_and_b32_e32 v157, 0xffff0000, v231
	v_pk_mul_f32 v[154:155], v[154:155], v[156:157]
	s_nop 0
	v_pk_mul_f32 v[136:137], v[136:137], v[154:155]
	v_lshlrev_b32_e32 v154, 16, v233
	v_and_b32_e32 v155, 0xffff0000, v233
	v_pk_mul_f32 v[152:153], v[152:153], v[154:155]
	s_nop 0
	v_pk_mul_f32 v[132:133], v[132:133], v[152:153]

; __device__ __forceinline__ float bflo(unsigned w) { return __uint_as_float(w << 16); }
; __device__ __forceinline__ float bfhi(unsigned w) { return __uint_as_float(w & 0xffff0000u); }
;     __device__ __forceinline__ void operator()(f32x4 (&acc)[2][2][4][2], const Unit& u, int wr, int wc, int fr, int fq) const {
;     ...
;             u32x4 g1v[2][2];
; #pragma unroll
;             for (int mm = 0; mm < 2; ++mm)
; #pragma unroll
;                 for (int bj = 0; bj < 2; ++bj) g1v[mm][bj] = *(const u32x4*)(gate + (size_t)(row0 + ai * HALF + (2 * mh + mm) * 16) * 2048 + 1024 + col0 + bj * HALF);
; #pragma unroll
;             for (int mm = 0; mm < 2; ++mm)
; #pragma unroll
;                 for (int bj = 0; bj < 2; ++bj) { const int m = 2 * mh + mm; const int r = row0 + ai * HALF + m * 16; const u32x4 g1 = g1v[mm][bj];
;                     const f32x4 g1a = {bflo(g1.x), bfhi(g1.x), bflo(g1.y), bfhi(g1.y)}, g1b = {bflo(g1.z), bfhi(g1.z), bflo(g1.w), bfhi(g1.w)};
;                     if (u.z == 0) {
;                         const u32x4 g0 = *(const u32x4*)(gate + (size_t)r * 2048 + col0 + bj * HALF);
;                         const f32x4 g0a = {bflo(g0.x), bfhi(g0.x), bflo(g0.y), bfhi(g0.y)}, g0b = {bflo(g0.z), bfhi(g0.z), bflo(g0.w), bfhi(g0.w)};
; #pragma unroll
;                         for (int i = 0; i < 4; ++i) { acc[ai][bj][m][0][i] *= g0a[i] * __builtin_amdgcn_rcpf(__builtin_fmaxf(g1a[i], 1e-30f)); acc[ai][bj][m][1][i] *= g0b[i] * __builtin_amdgcn_rcpf(__builtin_fmaxf(g1b[i], 1e-30f)); }
.LBB0_781:
	v_max_f32_e32 v156, v156, v156
	v_max_f32_e32 v157, v157, v157
	v_max_f32_e32 v156, 0xda24260, v156
	v_max_f32_e32 v157, 0xda24260, v157
	v_rcp_f32_e32 v156, v156
	v_max_f32_e32 v154, v154, v154
	v_rcp_f32_e32 v157, v157
	v_max_f32_e32 v146, v146, v146
	v_max_f32_e32 v147, v147, v147
	v_max_f32_e32 v154, 0xda24260, v154
	v_max_f32_e32 v146, 0xda24260, v146
	v_max_f32_e32 v147, 0xda24260, v147
	v_rcp_f32_e32 v154, v154
	v_rcp_f32_e32 v146, v146
	v_rcp_f32_e32 v147, v147
	s_waitcnt vmcnt(0)
	v_lshlrev_b32_e32 v174, 16, v234
	v_and_b32_e32 v175, 0xffff0000, v234
	v_max_f32_e32 v234, v155, v155
	v_max_f32_e32 v234, 0xda24260, v234
	v_rcp_f32_e32 v155, v234
	v_max_f32_e32 v234, v152, v152
	v_max_f32_e32 v234, 0xda24260, v234
	v_rcp_f32_e32 v152, v234
	v_max_f32_e32 v234, v153, v153
	v_max_f32_e32 v234, 0xda24260, v234
	v_rcp_f32_e32 v153, v234
	v_lshlrev_b32_e32 v234, 16, v235
	v_and_b32_e32 v235, 0xffff0000, v235
	v_pk_mul_f32 v[156:157], v[156:157], v[174:175]
	v_pk_mul_f32 v[234:235], v[152:153], v[234:235]
	v_pk_mul_f32 v[102:103], v[102:103], v[156:157]
	v_lshlrev_b32_e32 v156, 16, v236
	v_and_b32_e32 v157, 0xffff0000, v236
	v_pk_mul_f32 v[104:105], v[104:105], v[234:235]
	v_lshlrev_b32_e32 v234, 16, v237
	v_and_b32_e32 v235, 0xffff0000, v237
	v_pk_mul_f32 v[154:155], v[154:155], v[156:157]
	v_pk_mul_f32 v[146:147], v[146:147], v[234:235]
	v_pk_mul_f32 v[98:99], v[98:99], v[154:155]
	v_pk_mul_f32 v[100:101], v[100:101], v[146:147]
.LBB0_782:
	v_or_b32_e32 v182, 32, v170
	v_ashrrev_i32_e32 v183, 31, v182
	v_lshlrev_b64 v[146:147], 12, v[182:183]
	v_or_b32_e32 v176, 48, v170
	v_lshl_add_u64 v[146:147], s[46:47], 0, v[146:147]
	v_ashrrev_i32_e32 v177, 31, v176
	v_lshl_add_u64 v[184:185], v[146:147], 0, v[172:173]
	v_lshlrev_b64 v[146:147], 12, v[176:177]
	v_lshl_add_u64 v[146:147], s[46:47], 0, v[146:147]
	global_load_dwordx4 v[186:189], v[184:185], off offset:2048
	v_lshl_add_u64 v[174:175], v[146:147], 0, v[172:173]
	global_load_dwordx4 v[154:157], v[184:185], off offset:2304
	global_load_dwordx4 v[150:153], v[174:175], off offset:2048
	global_load_dwordx4 v[146:149], v[174:175], off offset:2304
	global_load_dwordx4 v[222:225], v[184:185], off
	global_load_dwordx4 v[226:229], v[184:185], off offset:256
	global_load_dwordx4 v[230:233], v[174:175], off
	global_load_dwordx4 v[234:237], v[174:175], off offset:256
	v_lshlrev_b64 v[182:183], 11, v[182:183]
	v_lshl_add_u64 v[182:183], s[52:53], 0, v[182:183]
	s_and_b64 vcc, exec, s[42:43]
	s_waitcnt vmcnt(3)
	v_lshlrev_b32_e32 v194, 16, v186
	v_and_b32_e32 v195, 0xffff0000, v186
	v_lshlrev_b32_e32 v190, 16, v187
	v_and_b32_e32 v191, 0xffff0000, v187
	v_lshlrev_b32_e32 v192, 16, v188
	v_and_b32_e32 v193, 0xffff0000, v188
	v_lshlrev_b32_e32 v188, 16, v189
	v_and_b32_e32 v189, 0xffff0000, v189
	v_lshl_add_u64 v[186:187], v[168:169], 1, v[182:183]
	s_cbranch_vccnz .LBB0_827
	v_pk_mul_f32 v[182:183], v[128:129], v[190:191]
	v_pk_mul_f32 v[200:201], v[126:127], v[194:195]
	v_pk_mul_f32 v[204:205], v[124:125], v[188:189]
	v_pk_mul_f32 v[202:203], v[122:123], v[192:193]
	v_cvt_pk_bf16_f32 v200, v200, v201
	v_cvt_pk_bf16_f32 v201, v182, v183
	v_cvt_pk_bf16_f32 v202, v202, v203
	v_cvt_pk_bf16_f32 v203, v204, v205
	global_store_dwordx4 v[186:187], v[200:203], off
	s_cbranch_execnz .LBB0_785
.LBB0_784:
	v_max_f32_e32 v171, v194, v194
	v_max_f32_e32 v171, 0xda24260, v171
	v_rcp_f32_e32 v182, v171
	v_max_f32_e32 v171, v192, v192
	v_max_f32_e32 v171, 0xda24260, v171
	v_rcp_f32_e32 v192, v171
	v_max_f32_e32 v171, v195, v195
	v_max_f32_e32 v171, 0xda24260, v171
	v_rcp_f32_e32 v183, v171
	v_max_f32_e32 v171, v193, v193
	v_max_f32_e32 v171, 0xda24260, v171
	v_rcp_f32_e32 v193, v171
	v_max_f32_e32 v171, v190, v190
	v_max_f32_e32 v171, 0xda24260, v171
	s_waitcnt vmcnt(0)
	v_lshlrev_b32_e32 v194, 16, v222
	v_and_b32_e32 v195, 0xffff0000, v222
	v_pk_mul_f32 v[182:183], v[182:183], v[194:195]
	v_lshlrev_b32_e32 v190, 16, v223
	v_pk_mul_f32 v[126:127], v[126:127], v[182:183]
	v_lshlrev_b32_e32 v182, 16, v224
	v_and_b32_e32 v183, 0xffff0000, v224
	v_pk_mul_f32 v[182:183], v[192:193], v[182:183]
	s_nop 0
	v_pk_mul_f32 v[122:123], v[122:123], v[182:183]
	v_rcp_f32_e32 v182, v171
	v_max_f32_e32 v171, v188, v188
	v_max_f32_e32 v171, 0xda24260, v171
	v_rcp_f32_e32 v188, v171
	v_max_f32_e32 v171, v191, v191
	v_max_f32_e32 v171, 0xda24260, v171
	v_rcp_f32_e32 v183, v171
	v_max_f32_e32 v171, v189, v189
	v_max_f32_e32 v171, 0xda24260, v171
	v_rcp_f32_e32 v189, v171
	v_and_b32_e32 v191, 0xffff0000, v223
	v_pk_mul_f32 v[182:183], v[182:183], v[190:191]
	s_nop 0
	v_pk_mul_f32 v[128:129], v[128:129], v[182:183]
	v_lshlrev_b32_e32 v182, 16, v225
	v_and_b32_e32 v183, 0xffff0000, v225
	v_pk_mul_f32 v[182:183], v[188:189], v[182:183]
	s_nop 0
	v_pk_mul_f32 v[124:125], v[124:125], v[182:183]

; __device__ __forceinline__ float bflo(unsigned w) { return __uint_as_float(w << 16); }
; __device__ __forceinline__ float bfhi(unsigned w) { return __uint_as_float(w & 0xffff0000u); }
;     __device__ __forceinline__ void operator()(f32x4 (&acc)[2][2][4][2], const Unit& u, int wr, int wc, int fr, int fq) const {
;     ...
;                 for (int bj = 0; bj < 2; ++bj) { const int m = 2 * mh + mm; const int r = row0 + ai * HALF + m * 16; const u32x4 g1 = g1v[mm][bj];
;                     const f32x4 g1a = {bflo(g1.x), bfhi(g1.x), bflo(g1.y), bfhi(g1.y)}, g1b = {bflo(g1.z), bfhi(g1.z), bflo(g1.w), bfhi(g1.w)};
;                     if (u.z == 0) {
;                         const u32x4 g0 = *(const u32x4*)(gate + (size_t)r * 2048 + col0 + bj * HALF);
;                         const f32x4 g0a = {bflo(g0.x), bfhi(g0.x), bflo(g0.y), bfhi(g0.y)}, g0b = {bflo(g0.z), bfhi(g0.z), bflo(g0.w), bfhi(g0.w)};
; #pragma unroll
;                         for (int i = 0; i < 4; ++i) { acc[ai][bj][m][0][i] *= g0a[i] * __builtin_amdgcn_rcpf(__builtin_fmaxf(g1a[i], 1e-30f)); acc[ai][bj][m][1][i] *= g0b[i] * __builtin_amdgcn_rcpf(__builtin_fmaxf(g1b[i], 1e-30f)); }
.LBB0_787:
	v_max_f32_e32 v157, v190, v190
	v_max_f32_e32 v157, 0xda24260, v157
	v_max_f32_e32 v156, v192, v192
	v_rcp_f32_e32 v182, v157
	v_max_f32_e32 v157, v193, v193
	v_max_f32_e32 v156, 0xda24260, v156
	v_max_f32_e32 v157, 0xda24260, v157
	v_rcp_f32_e32 v156, v156
	v_rcp_f32_e32 v157, v157
	v_max_f32_e32 v154, v154, v154
	v_max_f32_e32 v155, v155, v155
	v_max_f32_e32 v154, 0xda24260, v154
	v_max_f32_e32 v155, 0xda24260, v155
	v_rcp_f32_e32 v154, v154
	v_rcp_f32_e32 v155, v155
	s_waitcnt vmcnt(0)
	v_lshlrev_b32_e32 v192, 16, v226
	v_and_b32_e32 v193, 0xffff0000, v226
	v_pk_mul_f32 v[156:157], v[156:157], v[192:193]
	s_nop 0
	v_pk_mul_f32 v[94:95], v[94:95], v[156:157]
	v_max_f32_e32 v156, v191, v191
	v_max_f32_e32 v156, 0xda24260, v156
	v_rcp_f32_e32 v183, v156
	v_lshlrev_b32_e32 v156, 16, v228
	v_and_b32_e32 v157, 0xffff0000, v228
	v_pk_mul_f32 v[156:157], v[182:183], v[156:157]
	s_nop 0
	v_pk_mul_f32 v[90:91], v[90:91], v[156:157]
	v_max_f32_e32 v156, v188, v188
	v_max_f32_e32 v157, v189, v189
	v_max_f32_e32 v156, 0xda24260, v156
	v_max_f32_e32 v157, 0xda24260, v157
	v_rcp_f32_e32 v156, v156
	v_rcp_f32_e32 v157, v157
	v_lshlrev_b32_e32 v182, 16, v227
	v_and_b32_e32 v183, 0xffff0000, v227
	v_pk_mul_f32 v[156:157], v[156:157], v[182:183]
	s_nop 0
	v_pk_mul_f32 v[96:97], v[96:97], v[156:157]
	v_lshlrev_b32_e32 v156, 16, v229
	v_and_b32_e32 v157, 0xffff0000, v229
	v_pk_mul_f32 v[154:155], v[154:155], v[156:157]
	s_nop 0
	v_pk_mul_f32 v[92:93], v[92:93], v[154:155]

; __device__ __forceinline__ float bflo(unsigned w) { return __uint_as_float(w << 16); }
; __device__ __forceinline__ float bfhi(unsigned w) { return __uint_as_float(w & 0xffff0000u); }
;     __device__ __forceinline__ void operator()(f32x4 (&acc)[2][2][4][2], const Unit& u, int wr, int wc, int fr, int fq) const {
;     ...
;                 for (int bj = 0; bj < 2; ++bj) { const int m = 2 * mh + mm; const int r = row0 + ai * HALF + m * 16; const u32x4 g1 = g1v[mm][bj];
;                     const f32x4 g1a = {bflo(g1.x), bfhi(g1.x), bflo(g1.y), bfhi(g1.y)}, g1b = {bflo(g1.z), bfhi(g1.z), bflo(g1.w), bfhi(g1.w)};
;                     if (u.z == 0) {
;                         const u32x4 g0 = *(const u32x4*)(gate + (size_t)r * 2048 + col0 + bj * HALF);
;                         const f32x4 g0a = {bflo(g0.x), bfhi(g0.x), bflo(g0.y), bfhi(g0.y)}, g0b = {bflo(g0.z), bfhi(g0.z), bflo(g0.w), bfhi(g0.w)};
; #pragma unroll
;                         for (int i = 0; i < 4; ++i) { acc[ai][bj][m][0][i] *= g0a[i] * __builtin_amdgcn_rcpf(__builtin_fmaxf(g1a[i], 1e-30f)); acc[ai][bj][m][1][i] *= g0b[i] * __builtin_amdgcn_rcpf(__builtin_fmaxf(g1b[i], 1e-30f)); }
.LBB0_790:
	v_max_f32_e32 v171, v176, v176
	v_max_f32_e32 v171, 0xda24260, v171
	v_rcp_f32_e32 v176, v171
	v_max_f32_e32 v171, v177, v177
	v_max_f32_e32 v171, 0xda24260, v171
	v_max_f32_e32 v156, v156, v156
	v_rcp_f32_e32 v177, v171
	v_max_f32_e32 v157, v157, v157
	v_max_f32_e32 v156, 0xda24260, v156
	v_max_f32_e32 v157, 0xda24260, v157
	v_rcp_f32_e32 v156, v156
	v_rcp_f32_e32 v157, v157
	v_max_f32_e32 v154, v154, v154
	v_max_f32_e32 v155, v155, v155
	v_max_f32_e32 v154, 0xda24260, v154
	v_max_f32_e32 v155, 0xda24260, v155
	v_rcp_f32_e32 v154, v154
	v_max_f32_e32 v152, v152, v152
	v_rcp_f32_e32 v155, v155
	v_max_f32_e32 v153, v153, v153
	v_max_f32_e32 v152, 0xda24260, v152
	v_max_f32_e32 v153, 0xda24260, v153
	v_rcp_f32_e32 v152, v152
	v_rcp_f32_e32 v153, v153
	s_waitcnt vmcnt(0)
	v_lshlrev_b32_e32 v182, 16, v230
	v_and_b32_e32 v183, 0xffff0000, v230
	v_pk_mul_f32 v[176:177], v[176:177], v[182:183]
	s_nop 0
	v_pk_mul_f32 v[118:119], v[118:119], v[176:177]
	v_lshlrev_b32_e32 v176, 16, v232
	v_and_b32_e32 v177, 0xffff0000, v232
	v_pk_mul_f32 v[156:157], v[156:157], v[176:177]
	s_nop 0
	v_pk_mul_f32 v[114:115], v[114:115], v[156:157]
	v_lshlrev_b32_e32 v156, 16, v231
	v_and_b32_e32 v157, 0xffff0000, v231
	v_pk_mul_f32 v[154:155], v[154:155], v[156:157]
	s_nop 0
	v_pk_mul_f32 v[120:121], v[120:121], v[154:155]
	v_lshlrev_b32_e32 v154, 16, v233
	v_and_b32_e32 v155, 0xffff0000, v233
	v_pk_mul_f32 v[152:153], v[152:153], v[154:155]
	s_nop 0
	v_pk_mul_f32 v[116:117], v[116:117], v[152:153]

; __device__ __forceinline__ u32x4 pack8(const f32x4 a, const f32x4 b) { u32x4 w; w.x = cvt_pk_bf16(a[0], a[1]); w.y = cvt_pk_bf16(a[2], a[3]); w.z = cvt_pk_bf16(b[0], b[1]); w.w = cvt_pk_bf16(b[2], b[3]); return w; }
; __device__ __forceinline__ float bflo(unsigned w) { return __uint_as_float(w << 16); }
; __device__ __forceinline__ float bfhi(unsigned w) { return __uint_as_float(w & 0xffff0000u); }
;     __device__ __forceinline__ void operator()(f32x4 (&acc)[2][2][4][2], const Unit& u, int wr, int wc, int fr, int fq) const {
;     ...
;             u32x4 g1v[2][2];
; #pragma unroll
;             for (int mm = 0; mm < 2; ++mm)
; #pragma unroll
;                 for (int bj = 0; bj < 2; ++bj) g1v[mm][bj] = *(const u32x4*)(gate + (size_t)(row0 + ai * HALF + (2 * mh + mm) * 16) * 2048 + 1024 + col0 + bj * HALF);
; #pragma unroll
;             for (int mm = 0; mm < 2; ++mm)
; #pragma unroll
;                 for (int bj = 0; bj < 2; ++bj) { const int m = 2 * mh + mm; const int r = row0 + ai * HALF + m * 16; const u32x4 g1 = g1v[mm][bj];
;                     const f32x4 g1a = {bflo(g1.x), bfhi(g1.x), bflo(g1.y), bfhi(g1.y)}, g1b = {bflo(g1.z), bfhi(g1.z), bflo(g1.w), bfhi(g1.w)};
;                     if (u.z == 0) {
;                         const u32x4 g0 = *(const u32x4*)(gate + (size_t)r * 2048 + col0 + bj * HALF);
;                         const f32x4 g0a = {bflo(g0.x), bfhi(g0.x), bflo(g0.y), bfhi(g0.y)}, g0b = {bflo(g0.z), bfhi(g0.z), bflo(g0.w), bfhi(g0.w)};
; #pragma unroll
;                         for (int i = 0; i < 4; ++i) { acc[ai][bj][m][0][i] *= g0a[i] * __builtin_amdgcn_rcpf(__builtin_fmaxf(g1a[i], 1e-30f)); acc[ai][bj][m][1][i] *= g0b[i] * __builtin_amdgcn_rcpf(__builtin_fmaxf(g1b[i], 1e-30f)); }
;                     } else {
;                         *(u32x4*)(merged + (size_t)r * 1024 + col0 + bj * HALF) = pack8(acc[ai][bj][m][0] * g1a, acc[ai][bj][m][1] * g1b); }
.LBB0_793:
	v_max_f32_e32 v156, v156, v156
	v_max_f32_e32 v157, v157, v157
	v_max_f32_e32 v156, 0xda24260, v156
	v_max_f32_e32 v157, 0xda24260, v157
	v_rcp_f32_e32 v156, v156
	v_max_f32_e32 v154, v154, v154
	v_rcp_f32_e32 v157, v157
	v_max_f32_e32 v146, v146, v146
	v_max_f32_e32 v147, v147, v147
	v_max_f32_e32 v154, 0xda24260, v154
	v_max_f32_e32 v146, 0xda24260, v146
	v_max_f32_e32 v147, 0xda24260, v147
	v_rcp_f32_e32 v154, v154
	v_rcp_f32_e32 v146, v146
	v_rcp_f32_e32 v147, v147
	s_waitcnt vmcnt(0)
	v_lshlrev_b32_e32 v174, 16, v234
	v_and_b32_e32 v175, 0xffff0000, v234
	v_max_f32_e32 v234, v155, v155
	v_max_f32_e32 v234, 0xda24260, v234
	v_rcp_f32_e32 v155, v234
	v_max_f32_e32 v234, v152, v152
	v_max_f32_e32 v234, 0xda24260, v234
	v_rcp_f32_e32 v152, v234
	v_max_f32_e32 v234, v153, v153
	v_max_f32_e32 v234, 0xda24260, v234
	v_rcp_f32_e32 v153, v234
	v_lshlrev_b32_e32 v234, 16, v235
	v_and_b32_e32 v235, 0xffff0000, v235
	v_pk_mul_f32 v[156:157], v[156:157], v[174:175]
	v_pk_mul_f32 v[234:235], v[152:153], v[234:235]
	v_pk_mul_f32 v[86:87], v[86:87], v[156:157]
	v_lshlrev_b32_e32 v156, 16, v236
	v_and_b32_e32 v157, 0xffff0000, v236
	v_pk_mul_f32 v[88:89], v[88:89], v[234:235]
	v_lshlrev_b32_e32 v234, 16, v237
	v_and_b32_e32 v235, 0xffff0000, v237
	v_pk_mul_f32 v[154:155], v[154:155], v[156:157]
	v_pk_mul_f32 v[146:147], v[146:147], v[234:235]
	v_pk_mul_f32 v[82:83], v[82:83], v[154:155]
	v_pk_mul_f32 v[84:85], v[84:85], v[146:147]
.LBB0_794:
	v_add_u32_e32 v182, 0x80, v170
	v_ashrrev_i32_e32 v183, 31, v182
	v_lshlrev_b64 v[146:147], 12, v[182:183]
	v_add_u32_e32 v176, 0x90, v170
	v_lshl_add_u64 v[146:147], s[46:47], 0, v[146:147]
	v_ashrrev_i32_e32 v177, 31, v176
	v_lshl_add_u64 v[184:185], v[146:147], 0, v[172:173]
	v_lshlrev_b64 v[146:147], 12, v[176:177]
	v_lshl_add_u64 v[146:147], s[46:47], 0, v[146:147]
	global_load_dwordx4 v[186:189], v[184:185], off offset:2048
	v_lshl_add_u64 v[174:175], v[146:147], 0, v[172:173]
	global_load_dwordx4 v[154:157], v[184:185], off offset:2304
	global_load_dwordx4 v[150:153], v[174:175], off offset:2048
	global_load_dwordx4 v[146:149], v[174:175], off offset:2304
	global_load_dwordx4 v[222:225], v[184:185], off
	global_load_dwordx4 v[226:229], v[184:185], off offset:256
	global_load_dwordx4 v[230:233], v[174:175], off
	global_load_dwordx4 v[234:237], v[174:175], off offset:256
	v_lshlrev_b64 v[182:183], 11, v[182:183]
	v_lshl_add_u64 v[182:183], s[52:53], 0, v[182:183]
	s_and_b64 vcc, exec, s[42:43]
	s_waitcnt vmcnt(3)
	v_lshlrev_b32_e32 v194, 16, v186
	v_and_b32_e32 v195, 0xffff0000, v186
	v_lshlrev_b32_e32 v190, 16, v187
	v_and_b32_e32 v191, 0xffff0000, v187
	v_lshlrev_b32_e32 v192, 16, v188
	v_and_b32_e32 v193, 0xffff0000, v188
	v_lshlrev_b32_e32 v188, 16, v189
	v_and_b32_e32 v189, 0xffff0000, v189
	v_lshl_add_u64 v[186:187], v[168:169], 1, v[182:183]
	s_cbranch_vccnz .LBB0_831
	v_pk_mul_f32 v[182:183], v[80:81], v[190:191]
	v_pk_mul_f32 v[200:201], v[78:79], v[194:195]
	v_pk_mul_f32 v[204:205], v[76:77], v[188:189]
	v_pk_mul_f32 v[202:203], v[74:75], v[192:193]
	v_cvt_pk_bf16_f32 v200, v200, v201
	v_cvt_pk_bf16_f32 v201, v182, v183
	v_cvt_pk_bf16_f32 v202, v202, v203
	v_cvt_pk_bf16_f32 v203, v204, v205
	global_store_dwordx4 v[186:187], v[200:203], off
	s_cbranch_execnz .LBB0_797
.LBB0_796:
	v_max_f32_e32 v171, v194, v194
	v_max_f32_e32 v171, 0xda24260, v171
	v_rcp_f32_e32 v182, v171
	v_max_f32_e32 v171, v192, v192
	v_max_f32_e32 v171, 0xda24260, v171
	v_rcp_f32_e32 v192, v171
	v_max_f32_e32 v171, v195, v195
	v_max_f32_e32 v171, 0xda24260, v171
	v_rcp_f32_e32 v183, v171
	v_max_f32_e32 v171, v193, v193
	v_max_f32_e32 v171, 0xda24260, v171
	v_rcp_f32_e32 v193, v171
	v_max_f32_e32 v171, v190, v190
	v_max_f32_e32 v171, 0xda24260, v171
	s_waitcnt vmcnt(0)
	v_lshlrev_b32_e32 v194, 16, v222
	v_and_b32_e32 v195, 0xffff0000, v222
	v_pk_mul_f32 v[182:183], v[182:183], v[194:195]
	v_lshlrev_b32_e32 v190, 16, v223
	v_pk_mul_f32 v[78:79], v[78:79], v[182:183]
	v_lshlrev_b32_e32 v182, 16, v224
	v_and_b32_e32 v183, 0xffff0000, v224
	v_pk_mul_f32 v[182:183], v[192:193], v[182:183]
	s_nop 0
	v_pk_mul_f32 v[74:75], v[74:75], v[182:183]
	v_rcp_f32_e32 v182, v171
	v_max_f32_e32 v171, v188, v188
	v_max_f32_e32 v171, 0xda24260, v171
	v_rcp_f32_e32 v188, v171
	v_max_f32_e32 v171, v191, v191
	v_max_f32_e32 v171, 0xda24260, v171
	v_rcp_f32_e32 v183, v171
	v_max_f32_e32 v171, v189, v189
	v_max_f32_e32 v171, 0xda24260, v171
	v_rcp_f32_e32 v189, v171
	v_and_b32_e32 v191, 0xffff0000, v223
	v_pk_mul_f32 v[182:183], v[182:183], v[190:191]
	s_nop 0
	v_pk_mul_f32 v[80:81], v[80:81], v[182:183]
	v_lshlrev_b32_e32 v182, 16, v225
	v_and_b32_e32 v183, 0xffff0000, v225
	v_pk_mul_f32 v[182:183], v[188:189], v[182:183]
	s_nop 0
	v_pk_mul_f32 v[76:77], v[76:77], v[182:183]

; __device__ __forceinline__ float bflo(unsigned w) { return __uint_as_float(w << 16); }
; __device__ __forceinline__ float bfhi(unsigned w) { return __uint_as_float(w & 0xffff0000u); }
;     __device__ __forceinline__ void operator()(f32x4 (&acc)[2][2][4][2], const Unit& u, int wr, int wc, int fr, int fq) const {
;     ...
;                     if (u.z == 0) {
;                         const u32x4 g0 = *(const u32x4*)(gate + (size_t)r * 2048 + col0 + bj * HALF);
;                         const f32x4 g0a = {bflo(g0.x), bfhi(g0.x), bflo(g0.y), bfhi(g0.y)}, g0b = {bflo(g0.z), bfhi(g0.z), bflo(g0.w), bfhi(g0.w)};
; #pragma unroll
;                         for (int i = 0; i < 4; ++i) { acc[ai][bj][m][0][i] *= g0a[i] * __builtin_amdgcn_rcpf(__builtin_fmaxf(g1a[i], 1e-30f)); acc[ai][bj][m][1][i] *= g0b[i] * __builtin_amdgcn_rcpf(__builtin_fmaxf(g1b[i], 1e-30f)); }
.LBB0_799:
	v_max_f32_e32 v157, v190, v190
	v_max_f32_e32 v157, 0xda24260, v157
	v_max_f32_e32 v156, v192, v192
	v_rcp_f32_e32 v182, v157
	v_max_f32_e32 v157, v193, v193
	v_max_f32_e32 v156, 0xda24260, v156
	v_max_f32_e32 v157, 0xda24260, v157
	v_rcp_f32_e32 v156, v156
	v_rcp_f32_e32 v157, v157
	v_max_f32_e32 v154, v154, v154
	v_max_f32_e32 v155, v155, v155
	v_max_f32_e32 v154, 0xda24260, v154
	v_max_f32_e32 v155, 0xda24260, v155
	v_rcp_f32_e32 v154, v154
	v_rcp_f32_e32 v155, v155
	s_waitcnt vmcnt(0)
	v_lshlrev_b32_e32 v192, 16, v226
	v_and_b32_e32 v193, 0xffff0000, v226
	v_pk_mul_f32 v[156:157], v[156:157], v[192:193]
	s_nop 0
	v_pk_mul_f32 v[46:47], v[46:47], v[156:157]
	v_max_f32_e32 v156, v191, v191
	v_max_f32_e32 v156, 0xda24260, v156
	v_rcp_f32_e32 v183, v156
	v_lshlrev_b32_e32 v156, 16, v228
	v_and_b32_e32 v157, 0xffff0000, v228
	v_pk_mul_f32 v[156:157], v[182:183], v[156:157]
	s_nop 0
	v_pk_mul_f32 v[42:43], v[42:43], v[156:157]
	v_max_f32_e32 v156, v188, v188
	v_max_f32_e32 v157, v189, v189
	v_max_f32_e32 v156, 0xda24260, v156
	v_max_f32_e32 v157, 0xda24260, v157
	v_rcp_f32_e32 v156, v156
	v_rcp_f32_e32 v157, v157
	v_lshlrev_b32_e32 v182, 16, v227
	v_and_b32_e32 v183, 0xffff0000, v227
	v_pk_mul_f32 v[156:157], v[156:157], v[182:183]
	s_nop 0
	v_pk_mul_f32 v[48:49], v[48:49], v[156:157]
	v_lshlrev_b32_e32 v156, 16, v229
	v_and_b32_e32 v157, 0xffff0000, v229
	v_pk_mul_f32 v[154:155], v[154:155], v[156:157]
	s_nop 0
	v_pk_mul_f32 v[44:45], v[44:45], v[154:155]

; __device__ __forceinline__ float bflo(unsigned w) { return __uint_as_float(w << 16); }
; __device__ __forceinline__ float bfhi(unsigned w) { return __uint_as_float(w & 0xffff0000u); }
;     __device__ __forceinline__ void operator()(f32x4 (&acc)[2][2][4][2], const Unit& u, int wr, int wc, int fr, int fq) const {
;     ...
;                     if (u.z == 0) {
;                         const u32x4 g0 = *(const u32x4*)(gate + (size_t)r * 2048 + col0 + bj * HALF);
;                         const f32x4 g0a = {bflo(g0.x), bfhi(g0.x), bflo(g0.y), bfhi(g0.y)}, g0b = {bflo(g0.z), bfhi(g0.z), bflo(g0.w), bfhi(g0.w)};
; #pragma unroll
;                         for (int i = 0; i < 4; ++i) { acc[ai][bj][m][0][i] *= g0a[i] * __builtin_amdgcn_rcpf(__builtin_fmaxf(g1a[i], 1e-30f)); acc[ai][bj][m][1][i] *= g0b[i] * __builtin_amdgcn_rcpf(__builtin_fmaxf(g1b[i], 1e-30f)); }
.LBB0_802:
	v_max_f32_e32 v171, v176, v176
	v_max_f32_e32 v171, 0xda24260, v171
	v_rcp_f32_e32 v176, v171
	v_max_f32_e32 v171, v177, v177
	v_max_f32_e32 v171, 0xda24260, v171
	v_max_f32_e32 v156, v156, v156
	v_rcp_f32_e32 v177, v171
	v_max_f32_e32 v157, v157, v157
	v_max_f32_e32 v156, 0xda24260, v156
	v_max_f32_e32 v157, 0xda24260, v157
	v_rcp_f32_e32 v156, v156
	v_rcp_f32_e32 v157, v157
	v_max_f32_e32 v154, v154, v154
	v_max_f32_e32 v155, v155, v155
	v_max_f32_e32 v154, 0xda24260, v154
	v_max_f32_e32 v155, 0xda24260, v155
	v_rcp_f32_e32 v154, v154
	v_max_f32_e32 v152, v152, v152
	v_rcp_f32_e32 v155, v155
	v_max_f32_e32 v153, v153, v153
	v_max_f32_e32 v152, 0xda24260, v152
	v_max_f32_e32 v153, 0xda24260, v153
	v_rcp_f32_e32 v152, v152
	v_rcp_f32_e32 v153, v153
	s_waitcnt vmcnt(0)
	v_lshlrev_b32_e32 v182, 16, v230
	v_and_b32_e32 v183, 0xffff0000, v230
	v_pk_mul_f32 v[176:177], v[176:177], v[182:183]
	s_nop 0
	v_pk_mul_f32 v[70:71], v[70:71], v[176:177]
	v_lshlrev_b32_e32 v176, 16, v232
	v_and_b32_e32 v177, 0xffff0000, v232
	v_pk_mul_f32 v[156:157], v[156:157], v[176:177]
	s_nop 0
	v_pk_mul_f32 v[66:67], v[66:67], v[156:157]
	v_lshlrev_b32_e32 v156, 16, v231
	v_and_b32_e32 v157, 0xffff0000, v231
	v_pk_mul_f32 v[154:155], v[154:155], v[156:157]
	s_nop 0
	v_pk_mul_f32 v[72:73], v[72:73], v[154:155]
	v_lshlrev_b32_e32 v154, 16, v233
	v_and_b32_e32 v155, 0xffff0000, v233
	v_pk_mul_f32 v[152:153], v[152:153], v[154:155]
	s_nop 0
	v_pk_mul_f32 v[68:69], v[68:69], v[152:153]

; __device__ __forceinline__ u32x4 pack8(const f32x4 a, const f32x4 b) { u32x4 w; w.x = cvt_pk_bf16(a[0], a[1]); w.y = cvt_pk_bf16(a[2], a[3]); w.z = cvt_pk_bf16(b[0], b[1]); w.w = cvt_pk_bf16(b[2], b[3]); return w; }
; __device__ __forceinline__ float bflo(unsigned w) { return __uint_as_float(w << 16); }
; __device__ __forceinline__ float bfhi(unsigned w) { return __uint_as_float(w & 0xffff0000u); }
;     __device__ __forceinline__ void operator()(f32x4 (&acc)[2][2][4][2], const Unit& u, int wr, int wc, int fr, int fq) const {
;     ...
;             u32x4 g1v[2][2];
; #pragma unroll
;             for (int mm = 0; mm < 2; ++mm)
; #pragma unroll
;                 for (int bj = 0; bj < 2; ++bj) g1v[mm][bj] = *(const u32x4*)(gate + (size_t)(row0 + ai * HALF + (2 * mh + mm) * 16) * 2048 + 1024 + col0 + bj * HALF);
; #pragma unroll
;             for (int mm = 0; mm < 2; ++mm)
; #pragma unroll
;                 for (int bj = 0; bj < 2; ++bj) { const int m = 2 * mh + mm; const int r = row0 + ai * HALF + m * 16; const u32x4 g1 = g1v[mm][bj];
;                     const f32x4 g1a = {bflo(g1.x), bfhi(g1.x), bflo(g1.y), bfhi(g1.y)}, g1b = {bflo(g1.z), bfhi(g1.z), bflo(g1.w), bfhi(g1.w)};
;                     if (u.z == 0) {
;                         const u32x4 g0 = *(const u32x4*)(gate + (size_t)r * 2048 + col0 + bj * HALF);
;                         const f32x4 g0a = {bflo(g0.x), bfhi(g0.x), bflo(g0.y), bfhi(g0.y)}, g0b = {bflo(g0.z), bfhi(g0.z), bflo(g0.w), bfhi(g0.w)};
; #pragma unroll
;                         for (int i = 0; i < 4; ++i) { acc[ai][bj][m][0][i] *= g0a[i] * __builtin_amdgcn_rcpf(__builtin_fmaxf(g1a[i], 1e-30f)); acc[ai][bj][m][1][i] *= g0b[i] * __builtin_amdgcn_rcpf(__builtin_fmaxf(g1b[i], 1e-30f)); }
;                     } else {
;                         *(u32x4*)(merged + (size_t)r * 1024 + col0 + bj * HALF) = pack8(acc[ai][bj][m][0] * g1a, acc[ai][bj][m][1] * g1b); }
.LBB0_805:
	v_max_f32_e32 v156, v156, v156
	v_max_f32_e32 v157, v157, v157
	v_max_f32_e32 v156, 0xda24260, v156
	v_max_f32_e32 v157, 0xda24260, v157
	v_rcp_f32_e32 v156, v156
	v_max_f32_e32 v154, v154, v154
	v_rcp_f32_e32 v157, v157
	v_max_f32_e32 v146, v146, v146
	v_max_f32_e32 v147, v147, v147
	v_max_f32_e32 v154, 0xda24260, v154
	v_max_f32_e32 v146, 0xda24260, v146
	v_max_f32_e32 v147, 0xda24260, v147
	v_rcp_f32_e32 v154, v154
	v_rcp_f32_e32 v146, v146
	v_rcp_f32_e32 v147, v147
	s_waitcnt vmcnt(0)
	v_lshlrev_b32_e32 v174, 16, v234
	v_and_b32_e32 v175, 0xffff0000, v234
	v_max_f32_e32 v234, v155, v155
	v_max_f32_e32 v234, 0xda24260, v234
	v_rcp_f32_e32 v155, v234
	v_max_f32_e32 v234, v152, v152
	v_max_f32_e32 v234, 0xda24260, v234
	v_rcp_f32_e32 v152, v234
	v_max_f32_e32 v234, v153, v153
	v_max_f32_e32 v234, 0xda24260, v234
	v_rcp_f32_e32 v153, v234
	v_lshlrev_b32_e32 v234, 16, v235
	v_and_b32_e32 v235, 0xffff0000, v235
	v_pk_mul_f32 v[156:157], v[156:157], v[174:175]
	v_pk_mul_f32 v[234:235], v[152:153], v[234:235]
	v_pk_mul_f32 v[38:39], v[38:39], v[156:157]
	v_lshlrev_b32_e32 v156, 16, v236
	v_and_b32_e32 v157, 0xffff0000, v236
	v_pk_mul_f32 v[40:41], v[40:41], v[234:235]
	v_lshlrev_b32_e32 v234, 16, v237
	v_and_b32_e32 v235, 0xffff0000, v237
	v_pk_mul_f32 v[154:155], v[154:155], v[156:157]
	v_pk_mul_f32 v[146:147], v[146:147], v[234:235]
	v_pk_mul_f32 v[34:35], v[34:35], v[154:155]
	v_pk_mul_f32 v[36:37], v[36:37], v[146:147]
.LBB0_806:
	v_add_u32_e32 v182, 0xa0, v170
	v_ashrrev_i32_e32 v183, 31, v182
	v_lshlrev_b64 v[146:147], 12, v[182:183]
	v_add_u32_e32 v174, 0xb0, v170
	v_lshl_add_u64 v[146:147], s[46:47], 0, v[146:147]
	v_ashrrev_i32_e32 v175, 31, v174
	v_lshl_add_u64 v[176:177], v[146:147], 0, v[172:173]
	v_lshlrev_b64 v[146:147], 12, v[174:175]
	v_lshl_add_u64 v[146:147], s[46:47], 0, v[146:147]
	global_load_dwordx4 v[192:195], v[176:177], off offset:2048
	v_lshl_add_u64 v[170:171], v[146:147], 0, v[172:173]
	global_load_dwordx4 v[154:157], v[176:177], off offset:2304
	global_load_dwordx4 v[150:153], v[170:171], off offset:2048
	global_load_dwordx4 v[146:149], v[170:171], off offset:2304
	global_load_dwordx4 v[222:225], v[176:177], off
	global_load_dwordx4 v[226:229], v[176:177], off offset:256
	global_load_dwordx4 v[230:233], v[170:171], off
	global_load_dwordx4 v[234:237], v[170:171], off offset:256
	v_lshlrev_b64 v[172:173], 11, v[182:183]
	v_lshl_add_u64 v[172:173], s[52:53], 0, v[172:173]
	s_and_b64 vcc, exec, s[42:43]
	v_lshl_add_u64 v[172:173], v[168:169], 1, v[172:173]
	s_waitcnt vmcnt(3)
	v_lshlrev_b32_e32 v190, 16, v192
	v_and_b32_e32 v191, 0xffff0000, v192
	v_lshlrev_b32_e32 v186, 16, v193
	v_and_b32_e32 v187, 0xffff0000, v193
	v_lshlrev_b32_e32 v188, 16, v194
	v_and_b32_e32 v189, 0xffff0000, v194
	v_lshlrev_b32_e32 v184, 16, v195
	v_and_b32_e32 v185, 0xffff0000, v195
	s_cbranch_vccnz .LBB0_835
	v_pk_mul_f32 v[182:183], v[64:65], v[186:187]
	v_pk_mul_f32 v[192:193], v[62:63], v[190:191]
	v_pk_mul_f32 v[200:201], v[60:61], v[184:185]
	v_pk_mul_f32 v[194:195], v[58:59], v[188:189]
	v_cvt_pk_bf16_f32 v192, v192, v193
	v_cvt_pk_bf16_f32 v193, v182, v183
	v_cvt_pk_bf16_f32 v194, v194, v195
	v_cvt_pk_bf16_f32 v195, v200, v201
	global_store_dwordx4 v[172:173], v[192:195], off
	s_cbranch_execnz .LBB0_809
.LBB0_808:
	v_max_f32_e32 v178, v190, v190
	v_max_f32_e32 v178, 0xda24260, v178
	v_rcp_f32_e32 v182, v178
	v_max_f32_e32 v178, v188, v188
	v_max_f32_e32 v178, 0xda24260, v178
	v_rcp_f32_e32 v188, v178
	v_max_f32_e32 v178, v191, v191
	v_max_f32_e32 v178, 0xda24260, v178
	v_rcp_f32_e32 v183, v178
	v_max_f32_e32 v178, v189, v189
	v_max_f32_e32 v178, 0xda24260, v178
	v_rcp_f32_e32 v189, v178
	v_max_f32_e32 v178, v186, v186
	v_max_f32_e32 v178, 0xda24260, v178
	s_waitcnt vmcnt(0)
	v_lshlrev_b32_e32 v190, 16, v222
	v_and_b32_e32 v191, 0xffff0000, v222
	v_pk_mul_f32 v[182:183], v[182:183], v[190:191]
	v_lshlrev_b32_e32 v186, 16, v223
	v_pk_mul_f32 v[62:63], v[62:63], v[182:183]
	v_lshlrev_b32_e32 v182, 16, v224
	v_and_b32_e32 v183, 0xffff0000, v224
	v_pk_mul_f32 v[182:183], v[188:189], v[182:183]
	s_nop 0
	v_pk_mul_f32 v[58:59], v[58:59], v[182:183]
	v_rcp_f32_e32 v182, v178
	v_max_f32_e32 v178, v184, v184
	v_max_f32_e32 v178, 0xda24260, v178
	v_rcp_f32_e32 v184, v178
	v_max_f32_e32 v178, v187, v187
	v_max_f32_e32 v178, 0xda24260, v178
	v_rcp_f32_e32 v183, v178
	v_max_f32_e32 v178, v185, v185
	v_max_f32_e32 v178, 0xda24260, v178
	v_rcp_f32_e32 v185, v178
	v_and_b32_e32 v187, 0xffff0000, v223
	v_pk_mul_f32 v[182:183], v[182:183], v[186:187]
	s_nop 0
	v_pk_mul_f32 v[64:65], v[64:65], v[182:183]
	v_lshlrev_b32_e32 v182, 16, v225
	v_and_b32_e32 v183, 0xffff0000, v225
	v_pk_mul_f32 v[182:183], v[184:185], v[182:183]
	s_nop 0
	v_pk_mul_f32 v[60:61], v[60:61], v[182:183]

; __device__ __forceinline__ float bflo(unsigned w) { return __uint_as_float(w << 16); }
; __device__ __forceinline__ float bfhi(unsigned w) { return __uint_as_float(w & 0xffff0000u); }
;     __device__ __forceinline__ void operator()(f32x4 (&acc)[2][2][4][2], const Unit& u, int wr, int wc, int fr, int fq) const {
;     ...
;                     if (u.z == 0) {
;                         const u32x4 g0 = *(const u32x4*)(gate + (size_t)r * 2048 + col0 + bj * HALF);
;                         const f32x4 g0a = {bflo(g0.x), bfhi(g0.x), bflo(g0.y), bfhi(g0.y)}, g0b = {bflo(g0.z), bfhi(g0.z), bflo(g0.w), bfhi(g0.w)};
; #pragma unroll
;                         for (int i = 0; i < 4; ++i) { acc[ai][bj][m][0][i] *= g0a[i] * __builtin_amdgcn_rcpf(__builtin_fmaxf(g1a[i], 1e-30f)); acc[ai][bj][m][1][i] *= g0b[i] * __builtin_amdgcn_rcpf(__builtin_fmaxf(g1b[i], 1e-30f)); }
.LBB0_811:
	v_max_f32_e32 v157, v186, v186
	v_max_f32_e32 v157, 0xda24260, v157
	v_max_f32_e32 v156, v188, v188
	v_rcp_f32_e32 v172, v157
	v_max_f32_e32 v157, v189, v189
	v_max_f32_e32 v156, 0xda24260, v156
	v_max_f32_e32 v157, 0xda24260, v157
	v_rcp_f32_e32 v156, v156
	v_rcp_f32_e32 v157, v157
	v_max_f32_e32 v154, v154, v154
	v_max_f32_e32 v155, v155, v155
	v_max_f32_e32 v154, 0xda24260, v154
	v_max_f32_e32 v155, 0xda24260, v155
	v_rcp_f32_e32 v154, v154
	v_rcp_f32_e32 v155, v155
	s_waitcnt vmcnt(0)
	v_lshlrev_b32_e32 v176, 16, v226
	v_and_b32_e32 v177, 0xffff0000, v226
	v_pk_mul_f32 v[156:157], v[156:157], v[176:177]
	s_nop 0
	v_pk_mul_f32 v[30:31], v[30:31], v[156:157]
	v_max_f32_e32 v156, v187, v187
	v_max_f32_e32 v156, 0xda24260, v156
	v_rcp_f32_e32 v173, v156
	v_lshlrev_b32_e32 v156, 16, v228
	v_and_b32_e32 v157, 0xffff0000, v228
	v_pk_mul_f32 v[156:157], v[172:173], v[156:157]
	s_nop 0
	v_pk_mul_f32 v[26:27], v[26:27], v[156:157]
	v_max_f32_e32 v156, v184, v184
	v_max_f32_e32 v157, v185, v185
	v_max_f32_e32 v156, 0xda24260, v156
	v_max_f32_e32 v157, 0xda24260, v157
	v_rcp_f32_e32 v156, v156
	v_rcp_f32_e32 v157, v157
	v_lshlrev_b32_e32 v172, 16, v227
	v_and_b32_e32 v173, 0xffff0000, v227
	v_pk_mul_f32 v[156:157], v[156:157], v[172:173]
	s_nop 0
	v_pk_mul_f32 v[32:33], v[32:33], v[156:157]
	v_lshlrev_b32_e32 v156, 16, v229
	v_and_b32_e32 v157, 0xffff0000, v229
	v_pk_mul_f32 v[154:155], v[154:155], v[156:157]
	s_nop 0
	v_pk_mul_f32 v[28:29], v[28:29], v[154:155]

; __device__ __forceinline__ float bflo(unsigned w) { return __uint_as_float(w << 16); }
; __device__ __forceinline__ float bfhi(unsigned w) { return __uint_as_float(w & 0xffff0000u); }
;     __device__ __forceinline__ void operator()(f32x4 (&acc)[2][2][4][2], const Unit& u, int wr, int wc, int fr, int fq) const {
;     ...
;                     if (u.z == 0) {
;                         const u32x4 g0 = *(const u32x4*)(gate + (size_t)r * 2048 + col0 + bj * HALF);
;                         const f32x4 g0a = {bflo(g0.x), bfhi(g0.x), bflo(g0.y), bfhi(g0.y)}, g0b = {bflo(g0.z), bfhi(g0.z), bflo(g0.w), bfhi(g0.w)};
; #pragma unroll
;                         for (int i = 0; i < 4; ++i) { acc[ai][bj][m][0][i] *= g0a[i] * __builtin_amdgcn_rcpf(__builtin_fmaxf(g1a[i], 1e-30f)); acc[ai][bj][m][1][i] *= g0b[i] * __builtin_amdgcn_rcpf(__builtin_fmaxf(g1b[i], 1e-30f)); }
.LBB0_814:
	v_max_f32_e32 v168, v172, v172
	v_max_f32_e32 v169, v173, v173
	v_max_f32_e32 v168, 0xda24260, v168
	v_max_f32_e32 v169, 0xda24260, v169
	v_rcp_f32_e32 v168, v168
	v_max_f32_e32 v156, v156, v156
	v_rcp_f32_e32 v169, v169
	v_max_f32_e32 v157, v157, v157
	v_max_f32_e32 v156, 0xda24260, v156
	v_max_f32_e32 v157, 0xda24260, v157
	v_rcp_f32_e32 v156, v156
	v_rcp_f32_e32 v157, v157
	v_max_f32_e32 v154, v154, v154
	v_max_f32_e32 v155, v155, v155
	v_max_f32_e32 v154, 0xda24260, v154
	v_max_f32_e32 v155, 0xda24260, v155
	v_rcp_f32_e32 v154, v154
	v_max_f32_e32 v152, v152, v152
	v_rcp_f32_e32 v155, v155
	v_max_f32_e32 v153, v153, v153
	v_max_f32_e32 v152, 0xda24260, v152
	v_max_f32_e32 v153, 0xda24260, v153
	v_rcp_f32_e32 v152, v152
	v_rcp_f32_e32 v153, v153
	s_waitcnt vmcnt(0)
	v_lshlrev_b32_e32 v172, 16, v230
	v_and_b32_e32 v173, 0xffff0000, v230
	v_pk_mul_f32 v[168:169], v[168:169], v[172:173]
	s_nop 0
	v_pk_mul_f32 v[54:55], v[54:55], v[168:169]
	v_lshlrev_b32_e32 v168, 16, v232
	v_and_b32_e32 v169, 0xffff0000, v232
	v_pk_mul_f32 v[156:157], v[156:157], v[168:169]
	s_nop 0
	v_pk_mul_f32 v[50:51], v[50:51], v[156:157]
	v_lshlrev_b32_e32 v156, 16, v231
	v_and_b32_e32 v157, 0xffff0000, v231
	v_pk_mul_f32 v[154:155], v[154:155], v[156:157]
	s_nop 0
	v_pk_mul_f32 v[56:57], v[56:57], v[154:155]
	v_lshlrev_b32_e32 v154, 16, v233
	v_and_b32_e32 v155, 0xffff0000, v233
	v_pk_mul_f32 v[152:153], v[152:153], v[154:155]
	s_nop 0
	v_pk_mul_f32 v[52:53], v[52:53], v[152:153]

; __device__ __forceinline__ float bflo(unsigned w) { return __uint_as_float(w << 16); }
; __device__ __forceinline__ float bfhi(unsigned w) { return __uint_as_float(w & 0xffff0000u); }
;     __device__ __forceinline__ void operator()(f32x4 (&acc)[2][2][4][2], const Unit& u, int wr, int wc, int fr, int fq) const {
;     ...
;                     if (u.z == 0) {
;                         const u32x4 g0 = *(const u32x4*)(gate + (size_t)r * 2048 + col0 + bj * HALF);
;                         const f32x4 g0a = {bflo(g0.x), bfhi(g0.x), bflo(g0.y), bfhi(g0.y)}, g0b = {bflo(g0.z), bfhi(g0.z), bflo(g0.w), bfhi(g0.w)};
; #pragma unroll
;                         for (int i = 0; i < 4; ++i) { acc[ai][bj][m][0][i] *= g0a[i] * __builtin_amdgcn_rcpf(__builtin_fmaxf(g1a[i], 1e-30f)); acc[ai][bj][m][1][i] *= g0b[i] * __builtin_amdgcn_rcpf(__builtin_fmaxf(g1b[i], 1e-30f)); }
.LBB0_817:
	v_max_f32_e32 v156, v156, v156
	v_max_f32_e32 v157, v157, v157
	v_max_f32_e32 v156, 0xda24260, v156
	v_max_f32_e32 v157, 0xda24260, v157
	v_rcp_f32_e32 v156, v156
	v_max_f32_e32 v154, v154, v154
	v_rcp_f32_e32 v157, v157
	v_max_f32_e32 v146, v146, v146
	v_max_f32_e32 v147, v147, v147
	v_max_f32_e32 v154, 0xda24260, v154
	v_max_f32_e32 v146, 0xda24260, v146
	v_max_f32_e32 v147, 0xda24260, v147
	v_rcp_f32_e32 v154, v154
	v_rcp_f32_e32 v146, v146
	v_rcp_f32_e32 v147, v147
	s_waitcnt vmcnt(0)
	v_lshlrev_b32_e32 v168, 16, v234
	v_and_b32_e32 v169, 0xffff0000, v234
	v_max_f32_e32 v234, v155, v155
	v_max_f32_e32 v234, 0xda24260, v234
	v_rcp_f32_e32 v155, v234
	v_max_f32_e32 v234, v152, v152
	v_max_f32_e32 v234, 0xda24260, v234
	v_rcp_f32_e32 v152, v234
	v_max_f32_e32 v234, v153, v153
	v_max_f32_e32 v234, 0xda24260, v234
	v_rcp_f32_e32 v153, v234
	v_lshlrev_b32_e32 v234, 16, v235
	v_and_b32_e32 v235, 0xffff0000, v235
	v_pk_mul_f32 v[156:157], v[156:157], v[168:169]
	v_pk_mul_f32 v[234:235], v[152:153], v[234:235]
	v_pk_mul_f32 v[22:23], v[22:23], v[156:157]
	v_lshlrev_b32_e32 v156, 16, v236
	v_and_b32_e32 v157, 0xffff0000, v236
	v_pk_mul_f32 v[24:25], v[24:25], v[234:235]
	v_lshlrev_b32_e32 v234, 16, v237
	v_and_b32_e32 v235, 0xffff0000, v237
	v_pk_mul_f32 v[154:155], v[154:155], v[156:157]
	v_pk_mul_f32 v[146:147], v[146:147], v[234:235]
	v_pk_mul_f32 v[18:19], v[18:19], v[154:155]
	v_pk_mul_f32 v[20:21], v[20:21], v[146:147]
